# decode work queue hands out single tasks (was pairs): finer grain at the end of phase 3
# baseline (speedup 1.0000x reference)
; #define LAS __attribute__((address_space(3)))
; __device__ __forceinline__ unsigned xb_ld(unsigned* p)              { return __hip_atomic_load(p, __ATOMIC_RELAXED, __HIP_MEMORY_SCOPE_AGENT); }
; #define XB_SPIN(cond, bar) do { unsigned _sp = 0; while (cond) { __builtin_amdgcn_s_sleep(1); \
;     if ((++_sp & 255u) == 0u) { if (xb_ld(&(bar)[XB_TMO])) break; if (_sp > XB_SPIN_CAP) { atomicAdd(&(bar)[XB_TMO], 1u); break; } } } } while (0)
; __device__ __forceinline__ void sb_decode_wave_loop(const Params& P, float* lds) {
;     unsigned* qd = (unsigned*)(P.ws + WS_BAR) + QW_DEC;
;     const int lane = threadIdx.x & 63;
;     volatile LAS unsigned* scw = (volatile LAS unsigned*)((LAS unsigned char*)lds + SC_CTL_OFF_FWD);
;     unsigned nxt = 0u;
;     if (lane == 0) nxt = atomicAdd(qd, 2u);
; __device__ __forceinline__ void p3_scan_and_sb(const Params& P, float* lds) {
;     const int tid = threadIdx.x, lane = tid & 63, wave = tid >> 6;
;     unsigned* ctl = (unsigned*)(P.ws + WS_BAR);
;     __syncthreads();
;     if (blockIdx.x < 96) {
;         const int bh = blockIdx.x >> 2, quarter = blockIdx.x & 3, b = bh / RH, h = bh % RH;
;         volatile LAS unsigned* scw = (volatile LAS unsigned*)((LAS unsigned char*)lds + SC_CTL_OFF);
;         if (tid < 5) scw[tid] = 0u;
;         if (tid == 0) { XB_SPIN(xb_ld(ctl + QW_PREP_W) < (unsigned)NPREP, ctl); __builtin_amdgcn_fence(__ATOMIC_ACQUIRE, "agent"); asm volatile("s_waitcnt vmcnt(0)" ::: "memory"); }
;         __syncthreads();
;         scan_prompt_wave(P, (unsigned char*)lds, b, h, quarter);
;         if (wave >= 5 + SC_FREE_WAVES) {
;             constexpr unsigned NCHU = SEQ / SCH;
;             while (scw[1] < NCHU || scw[2] < NCHU || scw[3] < NCHU || scw[4] < NCHU) __builtin_amdgcn_s_sleep(32);
;         }
;     } else {
;         const int grp = wave >> 2, gw = wave & 3;
;         volatile LAS unsigned* gctl = (volatile LAS unsigned*)((LAS unsigned char*)lds + LDS_CTL + 32);
;         if (tid < 8) gctl[tid] = 0u;
;         __syncthreads();
;         sba::Grp4 G; G.ctr = gctl + grp; G.gen = 0u;
;         if (grp == 1) sb_decode_wave_loop(P, lds);
.LBB0_939:
	s_cmp_lt_i32 s60, 4
	s_cselect_b64 s[0:1], -1, 0
	s_cmp_gt_i32 s61, 3
	s_cselect_b64 s[2:3], -1, 0
	s_and_b64 s[34:35], s[0:1], s[2:3]
	s_andn2_b64 vcc, exec, s[34:35]
	s_cbranch_vccnz .LBB0_1576
	v_writelane_b32 v252, s34, 54
	s_cmpk_lt_u32 s56, 0x60
	v_and_b32_e32 v1, 63, v0
	v_writelane_b32 v252, s35, 55
	v_writelane_b32 v252, s80, 56
	s_cselect_b64 s[52:53], -1, 0
	s_cmpk_gt_u32 s56, 0x5f
	v_writelane_b32 v252, s81, 57
	v_writelane_b32 v252, s56, 53
	v_writelane_b32 v252, s60, 51
	s_mov_b64 s[0:1], -1
	s_waitcnt vmcnt(0)
	v_writelane_b32 v252, s61, 52
	s_barrier
	v_writelane_b32 v252, s57, 50
	s_cbranch_scc0 .LBB0_1203
	v_writelane_b32 v252, s52, 58
	v_cmp_gt_u32_e32 vcc, 8, v0
	s_nop 0
	v_writelane_b32 v252, s53, 59
	s_and_saveexec_b64 s[0:1], vcc
	v_lshl_add_u32 v2, v0, 2, 0
	v_add_u32_e32 v2, 0x26020, v2
	v_mov_b32_e32 v3, 0
	ds_write_b32 v2, v3
	s_or_b64 exec, exec, s[0:1]
	v_lshrrev_b32_e32 v94, 8, v0
	s_waitcnt lgkmcnt(0)
	s_barrier
	v_cmp_eq_u32_e32 vcc, 1, v94
	s_mov_b64 s[0:1], exec
	v_writelane_b32 v252, s0, 60
	s_nop 1
	v_writelane_b32 v252, s1, 61
	s_and_b64 s[0:1], s[0:1], vcc
	s_mov_b64 exec, s[0:1]
	s_cbranch_execz .LBB0_1092
	s_add_u32 s0, s78, 0x3900
	s_addc_u32 s1, s79, 0
	v_writelane_b32 v252, s0, 62
	v_mov_b32_e32 v95, 0
	v_cmp_eq_u32_e64 s[4:5], 0, v1
	v_writelane_b32 v252, s1, 63
	s_and_saveexec_b64 s[0:1], s[4:5]
	v_readlane_b32 s22, v252, 48
	v_readlane_b32 s23, v252, 49
	s_cbranch_execz .LBB0_948
	s_mov_b64 s[6:7], exec
	v_mbcnt_lo_u32_b32 v2, s6, 0
	v_mbcnt_hi_u32_b32 v2, s7, v2
	v_cmp_eq_u32_e32 vcc, 0, v2
	s_and_saveexec_b64 s[2:3], vcc
	s_cbranch_execz .LBB0_947
	s_bcnt1_i32_b64 s6, s[6:7]
	v_mov_b32_e32 v4, s6
	v_readlane_b32 s6, v252, 62
	v_mov_b32_e32 v3, 0
	v_readlane_b32 s7, v252, 63
	s_nop 4
	global_atomic_add v3, v3, v4, s[6:7] sc0

; __device__ __forceinline__ void sb_decode_wave_loop(const Params& P, float* lds) {
;     ...
;     for (;;) {
;         const int t = __builtin_amdgcn_readfirstlane((int)nxt);
;         if (t >= DEC_NTASK) break;
;         if (lane == 0) nxt = atomicAdd(qd, 2u);
.LBB0_951:
	v_readfirstlane_b32 s34, v95
	s_cmpk_gt_i32 s34, 0x5fff
	s_mov_b64 s[0:1], -1
	s_cbranch_scc1 .LBB0_950
	s_and_saveexec_b64 s[0:1], s[4:5]
	s_cbranch_execz .LBB0_956
	s_mov_b64 s[36:37], exec
	v_mbcnt_lo_u32_b32 v2, s36, 0
	v_mbcnt_hi_u32_b32 v2, s37, v2
	v_cmp_eq_u32_e32 vcc, 0, v2
	s_and_saveexec_b64 s[2:3], vcc
	s_cbranch_execz .LBB0_955
	s_bcnt1_i32_b64 s33, s[36:37]
	v_readlane_b32 s36, v252, 62
	v_mov_b32_e32 v3, s33
	v_readlane_b32 s37, v252, 63
	s_nop 4
	global_atomic_add v3, v83, v3, s[36:37] sc0

; __device__ __forceinline__ void sb_decode_wave_loop(const Params& P, float* lds) {
;     ...
;         if (blockIdx.x < 96 && scan_running) { sb_decode_task<4>(P, lds, t); sb_decode_task<4>(P, lds, t + 1); }
;         else if (thin) { sb_decode_task<8>(P, lds, t); sb_decode_task<8>(P, lds, t + 1); }
;         else { sb_decode_task<16>(P, lds, t); sb_decode_task<16>(P, lds, t + 1); }
.LBB0_1024:
	s_or_b64 exec, exec, s[0:1]
	s_branch .LBB0_949

; #define LAS __attribute__((address_space(3)))
; __device__ __forceinline__ void sb_decode_wave_loop(const Params& P, float* lds) {
;     unsigned* qd = (unsigned*)(P.ws + WS_BAR) + QW_DEC;
;     const int lane = threadIdx.x & 63;
;     volatile LAS unsigned* scw = (volatile LAS unsigned*)((LAS unsigned char*)lds + SC_CTL_OFF_FWD);
;     unsigned nxt = 0u;
;     if (lane == 0) nxt = atomicAdd(qd, 2u);
.LBB0_1261:
	s_add_u32 s0, s78, 0x3900
	s_addc_u32 s1, s79, 0
	v_writelane_b32 v252, s0, 62
	v_mov_b32_e32 v98, 0
	v_cmp_eq_u32_e64 s[4:5], 0, v1
	v_writelane_b32 v252, s1, 63
	s_and_saveexec_b64 s[0:1], s[4:5]
	s_cbranch_execz .LBB0_1265
	s_mov_b64 s[6:7], exec
	v_mbcnt_lo_u32_b32 v2, s6, 0
	v_mbcnt_hi_u32_b32 v2, s7, v2
	v_cmp_eq_u32_e32 vcc, 0, v2
	s_and_saveexec_b64 s[2:3], vcc
	s_cbranch_execz .LBB0_1264
	s_bcnt1_i32_b64 s6, s[6:7]
	v_mov_b32_e32 v4, s6
	v_readlane_b32 s6, v252, 62
	v_mov_b32_e32 v3, 0
	v_readlane_b32 s7, v252, 63
	s_nop 4
	global_atomic_add v3, v3, v4, s[6:7] sc0

; __device__ __forceinline__ void sb_decode_wave_loop(const Params& P, float* lds) {
;     ...
;     for (;;) {
;         const int t = __builtin_amdgcn_readfirstlane((int)nxt);
;         if (t >= DEC_NTASK) break;
;         if (lane == 0) nxt = atomicAdd(qd, 2u);
.LBB0_1269:
	v_readfirstlane_b32 s34, v98
	s_cmpk_gt_i32 s34, 0x5fff
	s_mov_b64 s[0:1], -1
	s_cbranch_scc1 .LBB0_1268
	s_and_saveexec_b64 s[0:1], s[4:5]
	s_cbranch_execz .LBB0_1274
	s_mov_b64 s[36:37], exec
	v_mbcnt_lo_u32_b32 v2, s36, 0
	v_mbcnt_hi_u32_b32 v2, s37, v2
	v_cmp_eq_u32_e32 vcc, 0, v2
	s_and_saveexec_b64 s[2:3], vcc
	s_cbranch_execz .LBB0_1273
	s_bcnt1_i32_b64 s33, s[36:37]
	v_readlane_b32 s30, v252, 62
	v_mov_b32_e32 v3, s33
	v_readlane_b32 s31, v252, 63
	s_nop 4
	global_atomic_add v3, v83, v3, s[30:31] sc0
